# grid seam barrier: non-leader workgroups poll the top-level generation word directly (one fewer release hop per seam)
# baseline (speedup 1.0000x reference)
.LBB0_189:
	global_atomic_add v3, v209, v243, s[94:95] sc0
	v_cvt_f32_u32_e32 v1, v2
	v_sub_u32_e32 v4, 0, v2
	v_rcp_iflag_f32_e32 v1, v1
	s_nop 0
	v_mul_f32_e32 v1, 0x4f7ffffe, v1
	v_cvt_u32_f32_e32 v1, v1
	v_mul_lo_u32 v4, v4, v1
	v_mul_hi_u32 v4, v1, v4
	v_add_u32_e32 v1, v1, v4
	s_waitcnt vmcnt(0)
	v_mul_hi_u32 v1, v3, v1
	v_mul_lo_u32 v4, v1, v2
	v_sub_u32_e32 v4, v3, v4
	v_add_u32_e32 v5, 1, v1
	v_cmp_ge_u32_e32 vcc, v4, v2
	v_add_u32_e32 v3, 1, v3
	s_nop 0
	v_cndmask_b32_e32 v1, v1, v5, vcc
	v_sub_u32_e32 v5, v4, v2
	v_cndmask_b32_e32 v4, v4, v5, vcc
	v_add_u32_e32 v5, 1, v1
	v_cmp_ge_u32_e32 vcc, v4, v2
	s_nop 1
	v_cndmask_b32_e32 v1, v1, v5, vcc
	v_mul_lo_u32 v4, v2, v1
	v_add_u32_e32 v2, v4, v2
	v_cmp_ne_u32_e32 vcc, v3, v2
	s_and_saveexec_b64 s[2:3], vcc
	s_xor_b64 s[24:25], exec, s[2:3]
	s_cbranch_execz .LBB0_203
	s_waitcnt lgkmcnt(0)
	global_load_dword v0, v209, s[52:53] sc1
	s_waitcnt vmcnt(0)
	v_cmp_eq_u32_e32 vcc, v0, v1
	s_and_saveexec_b64 s[26:27], vcc
	s_cbranch_execz .LBB0_202
	s_mov_b32 s2, 1
	s_mov_b64 s[28:29], 0
	s_branch .LBB0_193

.LBB0_197:
	global_load_dword v0, v209, s[52:53] sc1
	s_add_i32 s2, s2, 1
	s_mov_b64 s[36:37], -1
	s_waitcnt vmcnt(0)
	v_cmp_ne_u32_e32 vcc, v0, v1
	s_orn2_b64 s[34:35], vcc, exec
	s_branch .LBB0_192

.LBB0_259:
	global_atomic_add v3, v209, v243, s[94:95] sc0
	v_cvt_f32_u32_e32 v1, v2
	v_sub_u32_e32 v4, 0, v2
	v_rcp_iflag_f32_e32 v1, v1
	s_nop 0
	v_mul_f32_e32 v1, 0x4f7ffffe, v1
	v_cvt_u32_f32_e32 v1, v1
	v_mul_lo_u32 v4, v4, v1
	v_mul_hi_u32 v4, v1, v4
	v_add_u32_e32 v1, v1, v4
	s_waitcnt vmcnt(0)
	v_mul_hi_u32 v1, v3, v1
	v_mul_lo_u32 v4, v1, v2
	v_sub_u32_e32 v4, v3, v4
	v_add_u32_e32 v5, 1, v1
	v_cmp_ge_u32_e32 vcc, v4, v2
	v_add_u32_e32 v3, 1, v3
	s_nop 0
	v_cndmask_b32_e32 v1, v1, v5, vcc
	v_sub_u32_e32 v5, v4, v2
	v_cndmask_b32_e32 v4, v4, v5, vcc
	v_add_u32_e32 v5, 1, v1
	v_cmp_ge_u32_e32 vcc, v4, v2
	s_nop 1
	v_cndmask_b32_e32 v1, v1, v5, vcc
	v_mul_lo_u32 v4, v2, v1
	v_add_u32_e32 v2, v4, v2
	v_cmp_ne_u32_e32 vcc, v3, v2
	s_and_saveexec_b64 s[2:3], vcc
	s_xor_b64 s[22:23], exec, s[2:3]
	s_cbranch_execz .LBB0_273
	s_waitcnt lgkmcnt(0)
	global_load_dword v0, v209, s[52:53] sc1
	s_waitcnt vmcnt(0)
	v_cmp_eq_u32_e32 vcc, v0, v1
	s_and_saveexec_b64 s[24:25], vcc
	s_cbranch_execz .LBB0_272
	s_mov_b32 s2, 1
	s_mov_b64 s[26:27], 0
	s_branch .LBB0_263

.LBB0_267:
	global_load_dword v0, v209, s[52:53] sc1
	s_add_i32 s2, s2, 1
	s_mov_b64 s[34:35], -1
	s_waitcnt vmcnt(0)
	v_cmp_ne_u32_e32 vcc, v0, v1
	s_orn2_b64 s[30:31], vcc, exec
	s_branch .LBB0_262

.LBB0_526:
	global_atomic_add v3, v209, v243, s[94:95] sc0
	v_cvt_f32_u32_e32 v1, v2
	v_sub_u32_e32 v4, 0, v2
	v_rcp_iflag_f32_e32 v1, v1
	s_nop 0
	v_mul_f32_e32 v1, 0x4f7ffffe, v1
	v_cvt_u32_f32_e32 v1, v1
	v_mul_lo_u32 v4, v4, v1
	v_mul_hi_u32 v4, v1, v4
	v_add_u32_e32 v1, v1, v4
	s_waitcnt vmcnt(0)
	v_mul_hi_u32 v1, v3, v1
	v_mul_lo_u32 v4, v1, v2
	v_sub_u32_e32 v4, v3, v4
	v_add_u32_e32 v5, 1, v1
	v_cmp_ge_u32_e32 vcc, v4, v2
	v_add_u32_e32 v3, 1, v3
	s_nop 0
	v_cndmask_b32_e32 v1, v1, v5, vcc
	v_sub_u32_e32 v5, v4, v2
	v_cndmask_b32_e32 v4, v4, v5, vcc
	v_add_u32_e32 v5, 1, v1
	v_cmp_ge_u32_e32 vcc, v4, v2
	s_nop 1
	v_cndmask_b32_e32 v1, v1, v5, vcc
	v_mul_lo_u32 v4, v2, v1
	v_add_u32_e32 v2, v4, v2
	v_cmp_ne_u32_e32 vcc, v3, v2
	s_and_saveexec_b64 s[2:3], vcc
	s_xor_b64 s[24:25], exec, s[2:3]
	s_cbranch_execz .LBB0_540
	s_waitcnt lgkmcnt(0)
	global_load_dword v0, v209, s[52:53] sc1
	s_waitcnt vmcnt(0)
	v_cmp_eq_u32_e32 vcc, v0, v1
	s_and_saveexec_b64 s[26:27], vcc
	s_cbranch_execz .LBB0_539
	s_mov_b32 s0, 1
	s_mov_b64 s[28:29], 0
	s_branch .LBB0_530

.LBB0_534:
	global_load_dword v0, v209, s[52:53] sc1
	s_add_i32 s0, s0, 1
	s_mov_b64 s[36:37], -1
	s_waitcnt vmcnt(0)
	v_cmp_ne_u32_e32 vcc, v0, v1
	s_orn2_b64 s[34:35], vcc, exec
	s_branch .LBB0_529

.LBB0_811:
	global_atomic_add v3, v209, v243, s[94:95] sc0
	v_cvt_f32_u32_e32 v1, v2
	v_sub_u32_e32 v4, 0, v2
	v_rcp_iflag_f32_e32 v1, v1
	s_nop 0
	v_mul_f32_e32 v1, 0x4f7ffffe, v1
	v_cvt_u32_f32_e32 v1, v1
	v_mul_lo_u32 v4, v4, v1
	v_mul_hi_u32 v4, v1, v4
	v_add_u32_e32 v1, v1, v4
	s_waitcnt vmcnt(0)
	v_mul_hi_u32 v1, v3, v1
	v_mul_lo_u32 v4, v1, v2
	v_sub_u32_e32 v4, v3, v4
	v_add_u32_e32 v5, 1, v1
	v_cmp_ge_u32_e32 vcc, v4, v2
	v_add_u32_e32 v3, 1, v3
	s_nop 0
	v_cndmask_b32_e32 v1, v1, v5, vcc
	v_sub_u32_e32 v5, v4, v2
	v_cndmask_b32_e32 v4, v4, v5, vcc
	v_add_u32_e32 v5, 1, v1
	v_cmp_ge_u32_e32 vcc, v4, v2
	s_nop 1
	v_cndmask_b32_e32 v1, v1, v5, vcc
	v_mul_lo_u32 v4, v2, v1
	v_add_u32_e32 v2, v4, v2
	v_cmp_ne_u32_e32 vcc, v3, v2
	s_and_saveexec_b64 s[2:3], vcc
	s_xor_b64 s[22:23], exec, s[2:3]
	s_cbranch_execz .LBB0_825
	s_waitcnt lgkmcnt(0)
	global_load_dword v0, v209, s[52:53] sc1
	s_waitcnt vmcnt(0)
	v_cmp_eq_u32_e32 vcc, v0, v1
	s_and_saveexec_b64 s[24:25], vcc
	s_cbranch_execz .LBB0_824
	s_mov_b32 s0, 1
	s_mov_b64 s[26:27], 0
	s_branch .LBB0_815

.LBB0_819:
	global_load_dword v0, v209, s[52:53] sc1
	s_add_i32 s0, s0, 1
	s_mov_b64 s[34:35], -1
	s_waitcnt vmcnt(0)
	v_cmp_ne_u32_e32 vcc, v0, v1
	s_orn2_b64 s[30:31], vcc, exec
	s_branch .LBB0_814
